# LN phase-1 loop: modulation loads issued before next-row loads, counted vmcnt so row prefetch spans full iteration
# baseline (speedup 1.0000x reference)
; DI int otid() { int t = threadIdx.x & 255; asm volatile("" : "+v"(t)); return t; }
; DI int obid() { int t = blockIdx.x * 2 + __builtin_amdgcn_readfirstlane(threadIdx.x >> 8); asm volatile("" : "+s"(t)); return t; }
; DI int ogrid() { int t = gridDim.x * 2; asm volatile("" : "+s"(t)); return t; }
; DI void ln_phase(const Params& p, int mode, const float* g, const float* bb, const float* modl, int s_next, int nrows) {
;     const int tid_ = otid(); const int lane = tid_ & 63, wave = tid_ >> 6;
;     const int bid_ = obid(), G_ = ogrid();
;     const int stride = G_ * 4;
;     float4 g4[4], b4[4];
; #pragma unroll
;     for (int i = 0; i < 4; ++i) { g4[i] = make_float4(1.f, 1.f, 1.f, 1.f); b4[i] = make_float4(0.f, 0.f, 0.f, 0.f); }
;     if (mode != 0) {
; #pragma unroll
;         for (int i = 0; i < 4; ++i) { g4[i] = ((const float4*)g)[lane + 64 * i]; b4[i] = ((const float4*)bb)[lane + 64 * i]; }
;     }
;     int row = bid_ * 4 + wave;
;     float4 nxt[4];
;     if (row < nrows) {
;         const float* src = mode == 0 ? (row < NL ? p.x + (size_t)row * DM : p.ctx + (size_t)(row - NL) * DM) : xrow_ptr(p, row);
; #pragma unroll
;         for (int i = 0; i < 4; ++i) nxt[i] = ((const float4*)src)[lane + 64 * i];
;     }
;     for (; row < nrows; row += stride) {
; DI void run_phase(int ph, char* smem) {
;     KParams kp = (KParams)__builtin_amdgcn_kernarg_segment_ptr();
;     asm volatile("" : "+s"(kp));
;     ...
;     const Params p = *kp;
;     ...
;     const Params p{};
;     ...
;     const int bid = obid(), G = ogrid();
.LBB0_11:
	v_readfirstlane_b32 s4, v163
	s_lshr_b32 s16, s4, 8
	v_readlane_b32 s4, v252, 7
	v_readlane_b32 s0, v252, 1
	s_add_i32 s2, s16, s4
	v_readlane_b32 s4, v252, 8
	v_readlane_b32 s1, v252, 2
	v_readlane_b32 s5, v252, 9
	s_load_dword s4, s[4:5], 0x0
	s_movk_i32 s3, 0x1000
	v_writelane_b32 v253, s54, 0
	s_mov_b32 s17, 0x10000
	s_mov_b32 s8, s18
	v_writelane_b32 v253, s55, 1
	v_writelane_b32 v253, s2, 2
	s_waitcnt lgkmcnt(0)
	v_writelane_b32 v253, s4, 3
	s_lshl_b32 s4, s4, 1
	v_writelane_b32 v253, s4, 4
	s_load_dwordx16 s[76:91], s[0:1], 0x0
	s_load_dwordx16 s[52:67], s[0:1], 0x40
	v_writelane_b32 v253, s4, 5
	s_load_dwordx16 s[36:51], s[0:1], 0x80
	s_mov_b64 s[6:7], -1
	s_mov_b64 s[4:5], 0
	s_waitcnt lgkmcnt(0)
	v_writelane_b32 v253, s52, 6
	s_cmp_lt_i32 s18, 1
	s_mov_b32 s18, 0x107ff
	v_writelane_b32 v253, s53, 7
	v_writelane_b32 v253, s54, 8
	v_writelane_b32 v253, s55, 9
	v_writelane_b32 v253, s56, 10
	v_writelane_b32 v253, s57, 11
	v_writelane_b32 v253, s58, 12
	v_writelane_b32 v253, s59, 13
	v_writelane_b32 v253, s60, 14
	v_writelane_b32 v253, s61, 15
	v_writelane_b32 v253, s62, 16
	v_writelane_b32 v253, s63, 17
	v_writelane_b32 v253, s64, 18
	v_writelane_b32 v253, s65, 19
	v_writelane_b32 v253, s66, 20
	v_writelane_b32 v253, s67, 21
	v_writelane_b32 v253, s36, 22
	s_nop 1
	v_writelane_b32 v253, s37, 23
	v_writelane_b32 v253, s38, 24
	v_writelane_b32 v253, s39, 25
	v_writelane_b32 v253, s40, 26
	v_writelane_b32 v253, s41, 27
	v_writelane_b32 v253, s42, 28
	v_writelane_b32 v253, s43, 29
	v_writelane_b32 v253, s44, 30
	v_writelane_b32 v253, s45, 31
	v_writelane_b32 v253, s46, 32
	v_writelane_b32 v253, s47, 33
	v_writelane_b32 v253, s48, 34
	v_writelane_b32 v253, s49, 35
	v_writelane_b32 v253, s50, 36
	v_writelane_b32 v253, s51, 37
	s_load_dwordx16 s[52:67], s[0:1], 0xc0
	s_load_dwordx8 s[36:43], s[0:1], 0x100
	s_load_dwordx4 s[68:71], s[0:1], 0x120
	s_nop 0
	s_load_dwordx2 s[0:1], s[0:1], 0x140
	s_waitcnt lgkmcnt(0)
	v_writelane_b32 v253, s36, 38
	s_nop 1
	v_writelane_b32 v253, s37, 39
	v_writelane_b32 v253, s38, 40
	v_writelane_b32 v253, s39, 41
	v_writelane_b32 v253, s40, 42
	v_writelane_b32 v253, s41, 43
	v_writelane_b32 v253, s42, 44
	v_writelane_b32 v253, s43, 45
	v_writelane_b32 v253, s0, 46
	s_nop 1
	v_writelane_b32 v253, s1, 47
	s_mov_b64 s[0:1], 0
	s_cbranch_scc1 .LBB0_20
	s_cmp_eq_u32 s8, 1
	s_mov_b64 s[0:1], -1
	s_cbranch_scc0 .LBB0_19
	v_readfirstlane_b32 s0, v163
	s_lshr_b32 s0, s0, 8
	v_readlane_b32 s1, v252, 7
	v_mov_b32_e32 v0, v228
	s_add_i32 s0, s0, s1
	s_lshl_b32 s0, s0, 2
	v_ashrrev_i32_e32 v4, 6, v0
	v_add_u32_e32 v39, s0, v4
	s_mov_b32 s19, s8
	v_readlane_b32 s1, v253, 4
	v_cmp_gt_i32_e32 vcc, s25, v39
	s_and_saveexec_b64 s[6:7], vcc
	s_cbranch_execz .LBB0_18
	v_and_b32_e32 v32, 63, v0
	v_ashrrev_i32_e32 v0, 31, v39
	v_add_u32_e32 v2, 0xffff0000, v39
	v_cmp_gt_i32_e32 vcc, s17, v39
	v_mov_b32_e32 v3, s77
	v_mov_b32_e32 v5, s76
	v_cndmask_b32_e32 v1, 0, v0, vcc
	v_cndmask_b32_e32 v0, v2, v39, vcc
	v_mov_b32_e32 v2, s81
	v_cndmask_b32_e32 v3, v2, v3, vcc
	v_mov_b32_e32 v2, s80
	v_cndmask_b32_e32 v2, v2, v5, vcc
	v_lshlrev_b64 v[0:1], 12, v[0:1]
	v_lshl_add_u64 v[0:1], v[2:3], 0, v[0:1]
	v_lshlrev_b32_e32 v160, 4, v32
	v_lshl_add_u64 v[6:7], v[0:1], 0, v[160:161]
	global_load_dwordx4 v[0:3], v[6:7], off offset:3072
	global_load_dwordx4 v[12:15], v[6:7], off offset:2048
	global_load_dwordx4 v[20:23], v[6:7], off offset:1024
	global_load_dwordx4 v[28:31], v[6:7], off
	v_lshlrev_b32_e32 v5, 2, v32
	s_lshl_b32 s8, s1, 2
	s_waitcnt vmcnt(25)
	v_xor_b32_e32 v33, 0x80, v5
	v_xor_b32_e32 v44, 64, v5
	v_xor_b32_e32 v45, 32, v5
	v_xor_b32_e32 v46, 16, v5
	v_xor_b32_e32 v47, 8, v5
	v_xor_b32_e32 v48, 4, v5
	v_ashrrev_i32_e32 v5, 31, v4
	s_ashr_i32 s1, s0, 31
	v_lshl_add_u64 v[4:5], v[4:5], 0, s[0:1]
	v_lshlrev_b64 v[4:5], 11, v[4:5]
	v_lshl_or_b32 v4, v32, 3, v4
	v_or_b32_e32 v6, 64, v32
	v_or_b32_e32 v8, 0x80, v32
	v_or_b32_e32 v10, 0xc0, v32
	v_add_u32_e32 v34, s8, v39
	s_ashr_i32 s9, s8, 31
	v_lshl_add_u64 v[4:5], s[62:63], 0, v[4:5]
	s_mov_b64 s[0:1], 0x400
	v_ashrrev_i32_e32 v35, 31, v34
	v_lshl_add_u64 v[36:37], v[4:5], 0, s[0:1]
	s_lshl_b64 s[10:11], s[8:9], 11
	s_mov_b64 s[12:13], 0
	v_lshlrev_b32_e32 v38, 4, v6
	v_lshlrev_b32_e32 v40, 4, v8
	v_lshlrev_b32_e32 v42, 4, v10
	s_waitcnt vmcnt(0)
	s_branch .LBB0_16
; DI void ln_phase(const Params& p, int mode, const float* g, const float* bb, const float* modl, int s_next, int nrows) {
;     ...
;         float4 sh4[4], sc4[4];
;         if (mode != 2) {
;             const float* mrow = modl + (size_t)(row < NL ? (row >> 13) : 8) * 9216;
;             const float4* sh = (const float4*)(mrow + (3 * s_next) * 1024);
;             const float4* sc = (const float4*)(mrow + (3 * s_next + 1) * 1024);
; #pragma unroll
;             for (int i = 0; i < 4; ++i) { sh4[i] = sh[lane + 64 * i]; sc4[i] = sc[lane + 64 * i]; }
;         }
;         __builtin_amdgcn_sched_barrier(0);
;         if (mode != 0) {
;             float s = 0.f;
; #pragma unroll
;             for (int i = 0; i < 16; ++i) s += v[i];
;             const float mu = wave_sum(s, lane) * (1.f / DM);
;             float q = 0.f;
; #pragma unroll
;             for (int i = 0; i < 16; ++i) { v[i] -= mu; q += v[i] * v[i]; }
;             const float rs = rsqrtf(wave_sum(q, lane) * (1.f / DM) + EPSV);
;             if (mode == 1 && lane == 0) *(f32x2*)(p.STATS + (size_t)row * 2) = (f32x2){mu, rs};
; #pragma unroll
;             for (int i = 0; i < 4; ++i) {
;                 v[4 * i] = v[4 * i] * rs * g4[i].x + b4[i].x; v[4 * i + 1] = v[4 * i + 1] * rs * g4[i].y + b4[i].y;
;                 v[4 * i + 2] = v[4 * i + 2] * rs * g4[i].z + b4[i].z; v[4 * i + 3] = v[4 * i + 3] * rs * g4[i].w + b4[i].w;
;             }
;         }
;         if (mode == 2) {
; #pragma unroll
;             for (int i = 0; i < 4; ++i) ((float4*)dst)[lane + 64 * i] = make_float4(v[4 * i], v[4 * i + 1], v[4 * i + 2], v[4 * i + 3]);
;         }
;         if (mode != 2) {
;             float s = 0.f;
; #pragma unroll
;             for (int i = 0; i < 16; ++i) s += v[i];
;             const float mu = wave_sum(s, lane) * (1.f / DM);
;             float q = 0.f;
; #pragma unroll
;             for (int i = 0; i < 16; ++i) { v[i] -= mu; q += v[i] * v[i]; }
;             const float rs = rsqrtf(wave_sum(q, lane) * (1.f / DM) + EPSV);
;             bf16_t* hrow = p.H + (size_t)row * DM;
; #pragma unroll
;             for (int i = 0; i < 4; ++i) {
;                 const float4 a = sh4[i], c4 = sc4[i];
;                 u32x2 w;
;                 w.x = pk_bf16(v[4 * i] * rs * (1.f + c4.x) + a.x, v[4 * i + 1] * rs * (1.f + c4.y) + a.y);
.LBB0_15:
	s_or_b64 exec, exec, s[14:15]
	v_add_f32_e32 v39, 0, v28
	v_add_f32_e32 v39, v29, v39
	v_add_f32_e32 v39, v30, v39
	v_add_f32_e32 v39, v31, v39
	v_add_f32_e32 v39, v20, v39
	v_add_f32_e32 v39, v21, v39
	v_add_f32_e32 v39, v22, v39
	v_add_f32_e32 v39, v23, v39
	v_add_f32_e32 v39, v12, v39
	v_add_f32_e32 v39, v13, v39
	v_add_f32_e32 v39, v14, v39
	v_add_f32_e32 v39, v15, v39
	v_add_f32_e32 v39, v0, v39
	v_add_f32_e32 v39, v1, v39
	v_add_f32_e32 v39, v2, v39
	v_add_f32_e32 v39, v3, v39
	v_mov_b32_e32 v41, v39
	s_nop 1
	v_permlane32_swap_b32_e32 v41, v39
	s_and_b64 s[0:1], exec, vcc
	s_or_b64 s[12:13], s[0:1], s[12:13]
	s_waitcnt lgkmcnt(0)
	v_add_f32_e32 v39, v39, v41
	v_mov_b32_e32 v41, v39
	s_nop 1
	v_permlane16_swap_b32_e32 v41, v39
	s_waitcnt lgkmcnt(0)
	v_add_f32_e32 v39, v39, v41
	s_nop 1
	v_mov_b32_dpp v41, v39 row_ror:8 row_mask:0xf bank_mask:0xf
	s_waitcnt lgkmcnt(0)
	v_add_f32_e32 v39, v39, v41
	s_nop 1
	v_mov_b32_dpp v41, v39 row_ror:4 row_mask:0xf bank_mask:0xf
	s_waitcnt lgkmcnt(0)
	v_add_f32_e32 v39, v39, v41
	s_nop 1
	v_mov_b32_dpp v41, v39 quad_perm:[2,3,0,1] row_mask:0xf bank_mask:0xf
	s_waitcnt lgkmcnt(0)
	v_add_f32_e32 v39, v39, v41
	s_nop 1
	v_mov_b32_dpp v41, v39 quad_perm:[1,0,3,2] row_mask:0xf bank_mask:0xf
	s_waitcnt lgkmcnt(0)
	v_add_f32_e32 v39, v39, v41
	v_mul_f32_e32 v82, 0x3a800000, v39
	v_pk_add_f32 v[30:31], v[30:31], v[82:83] op_sel_hi:[1,0] neg_lo:[0,1] neg_hi:[0,1]
	v_pk_add_f32 v[28:29], v[28:29], v[82:83] op_sel_hi:[1,0] neg_lo:[0,1] neg_hi:[0,1]
	v_pk_add_f32 v[22:23], v[22:23], v[82:83] op_sel_hi:[1,0] neg_lo:[0,1] neg_hi:[0,1]
	v_pk_add_f32 v[20:21], v[20:21], v[82:83] op_sel_hi:[1,0] neg_lo:[0,1] neg_hi:[0,1]
	v_pk_add_f32 v[14:15], v[14:15], v[82:83] op_sel_hi:[1,0] neg_lo:[0,1] neg_hi:[0,1]
	v_pk_add_f32 v[12:13], v[12:13], v[82:83] op_sel_hi:[1,0] neg_lo:[0,1] neg_hi:[0,1]
	v_pk_add_f32 v[2:3], v[2:3], v[82:83] op_sel_hi:[1,0] neg_lo:[0,1] neg_hi:[0,1]
	v_pk_add_f32 v[0:1], v[0:1], v[82:83] op_sel_hi:[1,0] neg_lo:[0,1] neg_hi:[0,1]
	v_pk_mul_f32 v[82:83], v[30:31], v[30:31]
	v_pk_mul_f32 v[84:85], v[28:29], v[28:29]
	v_pk_mul_f32 v[86:87], v[22:23], v[22:23]
	v_pk_mul_f32 v[88:89], v[20:21], v[20:21]
	v_pk_mul_f32 v[90:91], v[14:15], v[14:15]
	v_pk_mul_f32 v[92:93], v[12:13], v[12:13]
	v_pk_mul_f32 v[94:95], v[2:3], v[2:3]
	v_pk_mul_f32 v[96:97], v[0:1], v[0:1]
	s_waitcnt vmcnt(11)
	v_pk_add_f32 v[50:51], v[50:51], 1.0 op_sel_hi:[1,0]
	v_pk_add_f32 v[52:53], v[52:53], 1.0 op_sel_hi:[1,0]
	s_waitcnt vmcnt(10)
	v_pk_add_f32 v[54:55], v[54:55], 1.0 op_sel_hi:[1,0]
	v_pk_add_f32 v[56:57], v[56:57], 1.0 op_sel_hi:[1,0]
	s_waitcnt vmcnt(7)
	v_pk_add_f32 v[66:67], v[66:67], 1.0 op_sel_hi:[1,0]
	v_pk_add_f32 v[68:69], v[68:69], 1.0 op_sel_hi:[1,0]
	s_waitcnt vmcnt(6)
	v_pk_add_f32 v[70:71], v[70:71], 1.0 op_sel_hi:[1,0]
	v_add_f32_e32 v39, v84, v85
	v_add_f32_e32 v39, v82, v39
	v_add_f32_e32 v39, v83, v39
	v_add_f32_e32 v39, v88, v39
	v_add_f32_e32 v39, v89, v39
	v_add_f32_e32 v39, v86, v39
	v_add_f32_e32 v39, v87, v39
	v_add_f32_e32 v39, v92, v39
	v_add_f32_e32 v39, v93, v39
	v_add_f32_e32 v39, v90, v39
	v_add_f32_e32 v39, v91, v39
	v_add_f32_e32 v39, v96, v39
	v_add_f32_e32 v39, v97, v39
	v_add_f32_e32 v39, v94, v39
	v_add_f32_e32 v39, v95, v39
	v_mov_b32_e32 v41, v39
	s_nop 1
	v_permlane32_swap_b32_e32 v41, v39
	v_pk_add_f32 v[72:73], v[72:73], 1.0 op_sel_hi:[1,0]
	v_lshl_add_u64 v[34:35], v[34:35], 0, s[8:9]
	s_waitcnt lgkmcnt(0)
	v_add_f32_e32 v39, v39, v41
	v_mov_b32_e32 v41, v39
	s_nop 1
	v_permlane16_swap_b32_e32 v41, v39
	s_waitcnt lgkmcnt(0)
	v_add_f32_e32 v39, v39, v41
	s_nop 1
	v_mov_b32_dpp v41, v39 row_ror:8 row_mask:0xf bank_mask:0xf
	s_waitcnt lgkmcnt(0)
	v_add_f32_e32 v39, v39, v41
	s_nop 1
	v_mov_b32_dpp v41, v39 row_ror:4 row_mask:0xf bank_mask:0xf
	s_waitcnt lgkmcnt(0)
	v_add_f32_e32 v39, v39, v41
	s_nop 1
	v_mov_b32_dpp v41, v39 quad_perm:[2,3,0,1] row_mask:0xf bank_mask:0xf
	s_waitcnt lgkmcnt(0)
	v_add_f32_e32 v39, v39, v41
	s_nop 1
	v_mov_b32_dpp v41, v39 quad_perm:[1,0,3,2] row_mask:0xf bank_mask:0xf
	s_waitcnt lgkmcnt(0)
	v_add_f32_e32 v39, v39, v41
	v_fmamk_f32 v39, v39, 0x3a800000, v162
	v_mul_f32_e32 v41, 0x4b800000, v39
	v_cmp_gt_f32_e32 vcc, s74, v39
	s_nop 1
	v_cndmask_b32_e32 v39, v39, v41, vcc
	v_rsq_f32_e32 v39, v39
	s_nop 0
	v_mul_f32_e32 v41, 0x45800000, v39
	v_cndmask_b32_e32 v82, v39, v41, vcc
	v_pk_mul_f32 v[28:29], v[28:29], v[82:83] op_sel_hi:[1,0]
	v_pk_mul_f32 v[30:31], v[30:31], v[82:83] op_sel_hi:[1,0]
	v_pk_mul_f32 v[20:21], v[20:21], v[82:83] op_sel_hi:[1,0]
	v_pk_mul_f32 v[22:23], v[22:23], v[82:83] op_sel_hi:[1,0]
	v_pk_mul_f32 v[12:13], v[12:13], v[82:83] op_sel_hi:[1,0]
	v_pk_mul_f32 v[14:15], v[14:15], v[82:83] op_sel_hi:[1,0]
	v_pk_mul_f32 v[0:1], v[0:1], v[82:83] op_sel_hi:[1,0]
	v_pk_mul_f32 v[2:3], v[2:3], v[82:83] op_sel_hi:[1,0]
	v_pk_fma_f32 v[28:29], v[50:51], v[28:29], v[58:59]
	v_pk_fma_f32 v[30:31], v[52:53], v[30:31], v[60:61]
	v_pk_fma_f32 v[20:21], v[54:55], v[20:21], v[62:63]
	v_pk_fma_f32 v[22:23], v[56:57], v[22:23], v[64:65]
	s_waitcnt vmcnt(5)
	v_pk_fma_f32 v[12:13], v[66:67], v[12:13], v[74:75]
	v_pk_fma_f32 v[14:15], v[68:69], v[14:15], v[76:77]
	s_waitcnt vmcnt(4)
	v_pk_fma_f32 v[0:1], v[70:71], v[0:1], v[78:79]
	v_pk_fma_f32 v[2:3], v[72:73], v[2:3], v[80:81]
	v_cvt_pk_bf16_f32 v28, v28, v29
	v_cvt_pk_bf16_f32 v29, v30, v31
	v_cvt_pk_bf16_f32 v20, v20, v21
	v_cvt_pk_bf16_f32 v21, v22, v23
	v_cvt_pk_bf16_f32 v12, v12, v13
	v_cvt_pk_bf16_f32 v13, v14, v15
	v_cvt_pk_bf16_f32 v0, v0, v1
	v_cvt_pk_bf16_f32 v1, v2, v3
	global_store_dwordx2 v[36:37], v[28:29], off offset:-1024
	global_store_dwordx2 v[36:37], v[20:21], off offset:-512
	global_store_dwordx2 v[36:37], v[12:13], off
	global_store_dwordx2 v[36:37], v[0:1], off offset:512
	v_lshl_add_u64 v[36:37], v[36:37], 0, s[10:11]
	v_mov_b32_e32 v39, v49
	s_waitcnt vmcnt(4)
	v_mov_b64_e32 v[2:3], v[26:27]
	v_mov_b64_e32 v[0:1], v[24:25]
	v_mov_b64_e32 v[14:15], v[18:19]
	v_mov_b64_e32 v[12:13], v[16:17]
	v_mov_b64_e32 v[22:23], v[10:11]
	v_mov_b64_e32 v[20:21], v[8:9]
	v_mov_b64_e32 v[30:31], v[6:7]
	v_mov_b64_e32 v[28:29], v[4:5]
	s_andn2_b64 exec, exec, s[12:13]
	s_cbranch_execz .LBB0_18
; DI void ln_phase(const Params& p, int mode, const float* g, const float* bb, const float* modl, int s_next, int nrows) {
;     ...
;     for (; row < nrows; row += stride) {
;         float* dst = xrow_ptr(p, row);
;         float v[16];
; #pragma unroll
;         for (int i = 0; i < 4; ++i) { v[4 * i] = nxt[i].x; v[4 * i + 1] = nxt[i].y; v[4 * i + 2] = nxt[i].z; v[4 * i + 3] = nxt[i].w; }
;         const int rown = row + stride;
;         if (rown < nrows) {
;             const float* srcn = mode == 0 ? (rown < NL ? p.x + (size_t)rown * DM : p.ctx + (size_t)(rown - NL) * DM) : xrow_ptr(p, rown);
; #pragma unroll
;             for (int i = 0; i < 4; ++i) nxt[i] = ((const float4*)srcn)[lane + 64 * i];
;         }
;         float4 sh4[4], sc4[4];
;         if (mode != 2) {
;             const float* mrow = modl + (size_t)(row < NL ? (row >> 13) : 8) * 9216;
;             const float4* sh = (const float4*)(mrow + (3 * s_next) * 1024);
;             const float4* sc = (const float4*)(mrow + (3 * s_next + 1) * 1024);
; #pragma unroll
;             for (int i = 0; i < 4; ++i) { sh4[i] = sh[lane + 64 * i]; sc4[i] = sc[lane + 64 * i]; }
.LBB0_16:
	v_add_u32_e32 v49, s8, v39
	v_cmp_gt_i32_e64 s[0:1], s25, v49
	v_cmp_lt_i32_e32 vcc, s18, v49
	v_lshlrev_b32_e32 v160, 4, v32
	s_waitcnt vmcnt(7)
	v_mov_b64_e32 v[26:27], v[2:3]
	v_mov_b64_e32 v[24:25], v[0:1]
	s_waitcnt vmcnt(6)
	v_mov_b64_e32 v[18:19], v[14:15]
	v_mov_b64_e32 v[16:17], v[12:13]
	s_waitcnt vmcnt(5)
	v_mov_b64_e32 v[10:11], v[22:23]
	v_mov_b64_e32 v[8:9], v[20:21]
	s_waitcnt vmcnt(4)
	v_mov_b64_e32 v[6:7], v[30:31]
	v_mov_b64_e32 v[4:5], v[28:29]
	v_min_i32_e32 v39, 0x10000, v39
	v_ashrrev_i32_e32 v39, 13, v39
	v_mul_hi_i32_i24_e32 v51, 0x9000, v39
	v_mul_i32_i24_e32 v50, 0x9000, v39
	v_lshl_add_u64 v[50:51], s[54:55], 0, v[50:51]
	s_mov_b64 s[98:99], 0x1000
	v_lshl_add_u64 v[52:53], v[50:51], 0, s[98:99]
	v_mov_b32_e32 v39, v161
	v_mov_b32_e32 v41, v161
	v_mov_b32_e32 v43, v161
	v_lshl_add_u64 v[78:79], v[50:51], 0, v[160:161]
	v_lshl_add_u64 v[50:51], v[52:53], 0, v[160:161]
	v_lshl_add_u64 v[54:55], v[52:53], 0, v[38:39]
	v_lshl_add_u64 v[66:67], v[52:53], 0, v[40:41]
	v_lshl_add_u64 v[70:71], v[52:53], 0, v[42:43]
	global_load_dwordx4 v[50:53], v[50:51], off
	s_nop 0
	global_load_dwordx4 v[54:57], v[54:55], off
	s_nop 0
	global_load_dwordx4 v[58:61], v[78:79], off
	global_load_dwordx4 v[62:65], v[78:79], off offset:1024
	s_nop 0
	global_load_dwordx4 v[66:69], v[66:67], off
	s_nop 0
	global_load_dwordx4 v[70:73], v[70:71], off
	s_nop 0
	global_load_dwordx4 v[74:77], v[78:79], off offset:2048
	s_nop 0
	global_load_dwordx4 v[78:81], v[78:79], off offset:3072
	s_and_saveexec_b64 s[14:15], s[0:1]
	s_cbranch_execz .Lln1_skip
	v_add_u32_e32 v4, 0xffff0000, v49
	v_cmp_gt_i32_e64 s[0:1], s17, v49
	v_mov_b32_e32 v6, s81
	v_mov_b32_e32 v7, s77
	v_cndmask_b32_e64 v5, 0, v35, s[0:1]
	v_cndmask_b32_e64 v4, v4, v34, s[0:1]
	v_cndmask_b32_e64 v7, v6, v7, s[0:1]
	v_mov_b32_e32 v6, s80
	v_mov_b32_e32 v8, s76
	v_cndmask_b32_e64 v6, v6, v8, s[0:1]
	v_lshlrev_b64 v[4:5], 12, v[4:5]
	v_lshl_add_u64 v[4:5], v[6:7], 0, v[4:5]
	v_lshl_add_u64 v[24:25], v[4:5], 0, v[160:161]
	global_load_dwordx4 v[4:7], v[24:25], off
	global_load_dwordx4 v[8:11], v[24:25], off offset:1024
	global_load_dwordx4 v[16:19], v[24:25], off offset:2048
	s_nop 0
	global_load_dwordx4 v[24:27], v[24:25], off offset:3072
	s_branch .LBB0_15
.Lln1_skip:
	s_waitcnt vmcnt(0)
	s_branch .LBB0_15
